# last norm phase: the 8 gate-logit row pieces of each batch staged by LDS-DMA into a wave-private LDS slot and read back with ds_read instead of 8 serial global loads
# speedup vs baseline: 1.0121x; 1.0094x over previous
.LBB0_359:
	s_and_b64 vcc, exec, s[22:23]
	s_cbranch_vccz .Lnm_nomul
	s_lshl_b32 s8, s69, 3
	v_lshlrev_b32_e32 v246, 4, v174
	v_add_u32_e32 v246, s8, v246
	v_lshl_add_u64 v[200:201], s[48:49], 0, v[94:95]
	s_mov_b32 s2, 0xfffffc00
	s_mov_b32 s3, -1
	v_lshl_add_u64 v[202:203], v[200:201], 0, s[2:3]
	s_mov_b32 m0, s8
	s_nop 0
	global_load_lds_dwordx4 v[202:203], off
	s_add_i32 m0, s8, 0x400
	s_nop 0
	global_load_lds_dwordx4 v[200:201], off
	s_add_i32 s2, s60, 1
	s_ashr_i32 s3, s2, 31
	s_lshl_b64 s[2:3], s[2:3], 11
	v_lshl_add_u64 v[200:201], v[88:89], 0, s[2:3]
	s_mov_b64 s[2:3], 0x400
	s_add_i32 m0, s8, 0x800
	s_nop 0
	global_load_lds_dwordx4 v[200:201], off
	v_lshl_add_u64 v[202:203], v[200:201], 0, s[2:3]
	s_add_i32 m0, s8, 0xc00
	s_nop 0
	global_load_lds_dwordx4 v[202:203], off
	v_lshl_add_u64 v[200:201], v[202:203], 0, s[2:3]
	s_add_i32 m0, s8, 0x1000
	s_nop 0
	global_load_lds_dwordx4 v[200:201], off
	v_lshl_add_u64 v[202:203], v[200:201], 0, s[2:3]
	s_add_i32 m0, s8, 0x1400
	s_nop 0
	global_load_lds_dwordx4 v[202:203], off
	v_lshl_add_u64 v[200:201], v[202:203], 0, s[2:3]
	s_add_i32 m0, s8, 0x1800
	s_nop 0
	global_load_lds_dwordx4 v[200:201], off
	v_lshl_add_u64 v[202:203], v[200:201], 0, s[2:3]
	s_add_i32 m0, s8, 0x1c00
	s_nop 0
	global_load_lds_dwordx4 v[202:203], off
.Lnm_nomul:
	s_brev_b32 s2, 48
	v_add_co_u32_e32 v24, vcc, s2, v100
	v_cndmask_b32_e64 v28, 0, 1, s[22:23]
	s_nop 0
	v_addc_co_u32_e32 v25, vcc, 0, v101, vcc
	global_load_dwordx4 v[20:23], v[24:25], off
	s_nop 0
	global_load_dwordx4 v[24:27], v[24:25], off offset:1024
	s_add_i32 s8, s60, 1
	s_ashr_i32 s9, s8, 31
	s_lshl_b64 s[8:9], s[8:9], 11
	v_lshl_add_u64 v[200:201], v[0:1], 0, s[8:9]
	s_mov_b64 s[8:9], 0x1000
	v_lshl_add_u64 v[202:203], v[200:201], 0, s[8:9]
	global_load_dwordx4 v[204:207], v[200:201], off
	global_load_dwordx4 v[208:211], v[200:201], off offset:1024
	global_load_dwordx4 v[212:215], v[200:201], off offset:2048
	global_load_dwordx4 v[216:219], v[200:201], off offset:3072
	global_load_dwordx4 v[220:223], v[202:203], off
	global_load_dwordx4 v[224:227], v[202:203], off offset:1024
	v_cmp_ne_u32_e64 s[42:43], 1, v28
	s_andn2_b64 vcc, exec, s[22:23]
	s_waitcnt vmcnt(7)
	v_lshlrev_b32_e32 v114, 16, v20
	v_and_b32_e32 v115, 0xffff0000, v20
	v_lshlrev_b32_e32 v116, 16, v21
	v_and_b32_e32 v117, 0xffff0000, v21
	v_lshlrev_b32_e32 v110, 16, v22
	v_and_b32_e32 v111, 0xffff0000, v22
	v_lshlrev_b32_e32 v112, 16, v23
	v_and_b32_e32 v113, 0xffff0000, v23
	s_waitcnt vmcnt(6)
	v_lshlrev_b32_e32 v106, 16, v24
	v_and_b32_e32 v107, 0xffff0000, v24
	v_lshlrev_b32_e32 v108, 16, v25
	v_and_b32_e32 v109, 0xffff0000, v25
	v_lshlrev_b32_e32 v102, 16, v26
	v_and_b32_e32 v103, 0xffff0000, v26
	v_lshlrev_b32_e32 v104, 16, v27
	v_and_b32_e32 v105, 0xffff0000, v27
	s_cbranch_vccnz .LBB0_361
	v_lshl_add_u64 v[24:25], s[48:49], 0, v[94:95]
	ds_read_b128 v[20:23], v246
	s_waitcnt lgkmcnt(0)
	v_lshlrev_b32_e32 v26, 16, v20
	v_and_b32_e32 v27, 0xffff0000, v20
	v_lshlrev_b32_e32 v28, 16, v21
	v_and_b32_e32 v29, 0xffff0000, v21
	v_mul_f32_e32 v20, 0xbfb8aa3b, v26
	v_mul_f32_e32 v21, 0xbfb8aa3b, v27
	v_exp_f32_e32 v20, v20
	v_exp_f32_e32 v21, v21
	v_lshlrev_b32_e32 v30, 16, v22
	v_and_b32_e32 v22, 0xffff0000, v22
	v_add_f32_e32 v20, 1.0, v20
	v_add_f32_e32 v21, 1.0, v21
	v_rcp_f32_e32 v20, v20
	v_rcp_f32_e32 v21, v21
	v_lshlrev_b32_e32 v31, 16, v23
	v_and_b32_e32 v23, 0xffff0000, v23
	v_pk_mul_f32 v[114:115], v[20:21], v[114:115]
	v_mul_f32_e32 v20, 0xbfb8aa3b, v28
	v_mul_f32_e32 v21, 0xbfb8aa3b, v29
	v_exp_f32_e32 v20, v20
	v_exp_f32_e32 v21, v21
	v_add_f32_e32 v20, 1.0, v20
	v_add_f32_e32 v21, 1.0, v21
	v_rcp_f32_e32 v20, v20
	v_rcp_f32_e32 v21, v21
	s_nop 0
	v_pk_mul_f32 v[116:117], v[20:21], v[116:117]
	v_mul_f32_e32 v20, 0xbfb8aa3b, v30
	v_mul_f32_e32 v21, 0xbfb8aa3b, v22
	v_exp_f32_e32 v20, v20
	v_exp_f32_e32 v21, v21
	v_add_f32_e32 v20, 1.0, v20
	v_add_f32_e32 v21, 1.0, v21
	v_rcp_f32_e32 v20, v20
	v_rcp_f32_e32 v21, v21
	s_nop 0
	v_pk_mul_f32 v[110:111], v[20:21], v[110:111]
	v_mul_f32_e32 v20, 0xbfb8aa3b, v31
	v_mul_f32_e32 v21, 0xbfb8aa3b, v23
	v_exp_f32_e32 v20, v20
	v_exp_f32_e32 v21, v21
	v_add_f32_e32 v20, 1.0, v20
	v_add_f32_e32 v21, 1.0, v21
	v_rcp_f32_e32 v20, v20
	v_rcp_f32_e32 v21, v21
	s_nop 0
	v_pk_mul_f32 v[112:113], v[20:21], v[112:113]
	ds_read_b128 v[20:23], v246 offset:1024
	s_waitcnt lgkmcnt(0)
	v_lshlrev_b32_e32 v24, 16, v20
	v_and_b32_e32 v25, 0xffff0000, v20
	v_lshlrev_b32_e32 v26, 16, v21
	v_and_b32_e32 v27, 0xffff0000, v21
	v_mul_f32_e32 v20, 0xbfb8aa3b, v24
	v_mul_f32_e32 v21, 0xbfb8aa3b, v25
	v_exp_f32_e32 v20, v20
	v_exp_f32_e32 v21, v21
	v_lshlrev_b32_e32 v28, 16, v22
	v_and_b32_e32 v22, 0xffff0000, v22
	v_add_f32_e32 v20, 1.0, v20
	v_add_f32_e32 v21, 1.0, v21
	v_rcp_f32_e32 v20, v20
	v_rcp_f32_e32 v21, v21
	v_lshlrev_b32_e32 v29, 16, v23
	v_and_b32_e32 v23, 0xffff0000, v23
	v_pk_mul_f32 v[106:107], v[20:21], v[106:107]
	v_mul_f32_e32 v20, 0xbfb8aa3b, v26
	v_mul_f32_e32 v21, 0xbfb8aa3b, v27
	v_exp_f32_e32 v20, v20
	v_exp_f32_e32 v21, v21
	v_add_f32_e32 v20, 1.0, v20
	v_add_f32_e32 v21, 1.0, v21
	v_rcp_f32_e32 v20, v20
	v_rcp_f32_e32 v21, v21
	s_nop 0
	v_pk_mul_f32 v[108:109], v[20:21], v[108:109]
	v_mul_f32_e32 v20, 0xbfb8aa3b, v28
	v_mul_f32_e32 v21, 0xbfb8aa3b, v22
	v_exp_f32_e32 v20, v20
	v_exp_f32_e32 v21, v21
	v_add_f32_e32 v20, 1.0, v20
	v_add_f32_e32 v21, 1.0, v21
	v_rcp_f32_e32 v20, v20
	v_rcp_f32_e32 v21, v21
	s_nop 0
	v_pk_mul_f32 v[102:103], v[20:21], v[102:103]
	v_mul_f32_e32 v20, 0xbfb8aa3b, v29
	v_mul_f32_e32 v21, 0xbfb8aa3b, v23
	v_exp_f32_e32 v20, v20
	v_exp_f32_e32 v21, v21
	v_add_f32_e32 v20, 1.0, v20
	v_add_f32_e32 v21, 1.0, v21
	v_rcp_f32_e32 v20, v20
	v_rcp_f32_e32 v21, v21
	s_nop 0
	v_pk_mul_f32 v[104:105], v[20:21], v[104:105]

.LBB0_364:
	s_and_b64 vcc, exec, s[42:43]
	s_waitcnt vmcnt(2)
	v_mov_b32_e32 v36, v204
	v_mov_b32_e32 v37, v205
	v_mov_b32_e32 v38, v206
	v_mov_b32_e32 v39, v207
	v_mov_b32_e32 v40, v208
	v_mov_b32_e32 v41, v209
	v_mov_b32_e32 v42, v210
	v_mov_b32_e32 v43, v211
	v_lshlrev_b32_e32 v130, 16, v36
	v_and_b32_e32 v131, 0xffff0000, v36
	v_lshlrev_b32_e32 v140, 16, v37
	v_and_b32_e32 v141, 0xffff0000, v37
	v_lshlrev_b32_e32 v118, 16, v38
	v_and_b32_e32 v119, 0xffff0000, v38
	v_lshlrev_b32_e32 v120, 16, v39
	v_and_b32_e32 v121, 0xffff0000, v39
	s_waitcnt vmcnt(2)
	v_lshlrev_b32_e32 v122, 16, v40
	v_and_b32_e32 v123, 0xffff0000, v40
	v_lshlrev_b32_e32 v124, 16, v41
	v_and_b32_e32 v125, 0xffff0000, v41
	v_lshlrev_b32_e32 v126, 16, v42
	v_and_b32_e32 v127, 0xffff0000, v42
	v_lshlrev_b32_e32 v128, 16, v43
	v_and_b32_e32 v129, 0xffff0000, v43
	s_cbranch_vccnz .LBB0_366
	v_lshl_add_u64 v[40:41], v[88:89], 0, s[52:53]
	ds_read_b128 v[36:39], v246 offset:2048
	s_waitcnt lgkmcnt(0)
	v_lshlrev_b32_e32 v42, 16, v36
	v_and_b32_e32 v43, 0xffff0000, v36
	v_lshlrev_b32_e32 v44, 16, v37
	v_and_b32_e32 v45, 0xffff0000, v37
	v_mul_f32_e32 v36, 0xbfb8aa3b, v42
	v_mul_f32_e32 v37, 0xbfb8aa3b, v43
	v_exp_f32_e32 v36, v36
	v_exp_f32_e32 v37, v37
	v_lshlrev_b32_e32 v46, 16, v38
	v_and_b32_e32 v38, 0xffff0000, v38
	v_add_f32_e32 v36, 1.0, v36
	v_add_f32_e32 v37, 1.0, v37
	v_rcp_f32_e32 v36, v36
	v_rcp_f32_e32 v37, v37
	v_lshlrev_b32_e32 v47, 16, v39
	v_and_b32_e32 v39, 0xffff0000, v39
	v_pk_mul_f32 v[130:131], v[36:37], v[130:131]
	v_mul_f32_e32 v36, 0xbfb8aa3b, v44
	v_mul_f32_e32 v37, 0xbfb8aa3b, v45
	v_exp_f32_e32 v36, v36
	v_exp_f32_e32 v37, v37
	v_add_f32_e32 v36, 1.0, v36
	v_add_f32_e32 v37, 1.0, v37
	v_rcp_f32_e32 v36, v36
	v_rcp_f32_e32 v37, v37
	s_nop 0
	v_pk_mul_f32 v[140:141], v[36:37], v[140:141]
	v_mul_f32_e32 v36, 0xbfb8aa3b, v46
	v_mul_f32_e32 v37, 0xbfb8aa3b, v38
	v_exp_f32_e32 v36, v36
	v_exp_f32_e32 v37, v37
	v_add_f32_e32 v36, 1.0, v36
	v_add_f32_e32 v37, 1.0, v37
	v_rcp_f32_e32 v36, v36
	v_rcp_f32_e32 v37, v37
	s_nop 0
	v_pk_mul_f32 v[118:119], v[36:37], v[118:119]
	v_mul_f32_e32 v36, 0xbfb8aa3b, v47
	v_mul_f32_e32 v37, 0xbfb8aa3b, v39
	v_exp_f32_e32 v36, v36
	v_exp_f32_e32 v37, v37
	v_add_f32_e32 v36, 1.0, v36
	v_add_f32_e32 v37, 1.0, v37
	v_rcp_f32_e32 v36, v36
	v_rcp_f32_e32 v37, v37
	s_nop 0
	v_pk_mul_f32 v[120:121], v[36:37], v[120:121]
	ds_read_b128 v[36:39], v246 offset:3072
	s_waitcnt lgkmcnt(0)
	v_lshlrev_b32_e32 v40, 16, v36
	v_and_b32_e32 v41, 0xffff0000, v36
	v_lshlrev_b32_e32 v42, 16, v37
	v_and_b32_e32 v43, 0xffff0000, v37
	v_mul_f32_e32 v36, 0xbfb8aa3b, v40
	v_mul_f32_e32 v37, 0xbfb8aa3b, v41
	v_exp_f32_e32 v36, v36
	v_exp_f32_e32 v37, v37
	v_lshlrev_b32_e32 v44, 16, v38
	v_and_b32_e32 v38, 0xffff0000, v38
	v_add_f32_e32 v36, 1.0, v36
	v_add_f32_e32 v37, 1.0, v37
	v_rcp_f32_e32 v36, v36
	v_rcp_f32_e32 v37, v37
	v_lshlrev_b32_e32 v45, 16, v39
	v_and_b32_e32 v39, 0xffff0000, v39
	v_pk_mul_f32 v[122:123], v[36:37], v[122:123]
	v_mul_f32_e32 v36, 0xbfb8aa3b, v42
	v_mul_f32_e32 v37, 0xbfb8aa3b, v43
	v_exp_f32_e32 v36, v36
	v_exp_f32_e32 v37, v37
	v_add_f32_e32 v36, 1.0, v36
	v_add_f32_e32 v37, 1.0, v37
	v_rcp_f32_e32 v36, v36
	v_rcp_f32_e32 v37, v37
	s_nop 0
	v_pk_mul_f32 v[124:125], v[36:37], v[124:125]
	v_mul_f32_e32 v36, 0xbfb8aa3b, v44
	v_mul_f32_e32 v37, 0xbfb8aa3b, v38
	v_exp_f32_e32 v36, v36
	v_exp_f32_e32 v37, v37
	v_add_f32_e32 v36, 1.0, v36
	v_add_f32_e32 v37, 1.0, v37
	v_rcp_f32_e32 v36, v36
	v_rcp_f32_e32 v37, v37
	s_nop 0
	v_pk_mul_f32 v[126:127], v[36:37], v[126:127]
	v_mul_f32_e32 v36, 0xbfb8aa3b, v45
	v_mul_f32_e32 v37, 0xbfb8aa3b, v39
	v_exp_f32_e32 v36, v36
	v_exp_f32_e32 v37, v37
	v_add_f32_e32 v36, 1.0, v36
	v_add_f32_e32 v37, 1.0, v37
	v_rcp_f32_e32 v36, v36
	v_rcp_f32_e32 v37, v37
	s_nop 0
	v_pk_mul_f32 v[128:129], v[36:37], v[128:129]

.LBB0_369:
	s_and_b64 vcc, exec, s[42:43]
	s_waitcnt vmcnt(2)
	v_mov_b32_e32 v52, v212
	v_mov_b32_e32 v53, v213
	v_mov_b32_e32 v54, v214
	v_mov_b32_e32 v55, v215
	v_mov_b32_e32 v56, v216
	v_mov_b32_e32 v57, v217
	v_mov_b32_e32 v58, v218
	v_mov_b32_e32 v59, v219
	global_load_dwordx4 v[204:207], v[90:91], off offset:16
	global_load_dwordx4 v[208:211], v[90:91], off
	global_load_dwordx4 v[212:215], v[90:91], off offset:2064
	global_load_dwordx4 v[216:219], v[90:91], off offset:2048
	v_lshlrev_b32_e32 v154, 16, v52
	v_and_b32_e32 v155, 0xffff0000, v52
	v_lshlrev_b32_e32 v156, 16, v53
	v_and_b32_e32 v157, 0xffff0000, v53
	v_lshlrev_b32_e32 v142, 16, v54
	v_and_b32_e32 v143, 0xffff0000, v54
	v_lshlrev_b32_e32 v144, 16, v55
	v_and_b32_e32 v145, 0xffff0000, v55
	s_waitcnt vmcnt(6)
	v_lshlrev_b32_e32 v146, 16, v56
	v_and_b32_e32 v147, 0xffff0000, v56
	v_lshlrev_b32_e32 v148, 16, v57
	v_and_b32_e32 v149, 0xffff0000, v57
	v_lshlrev_b32_e32 v150, 16, v58
	v_and_b32_e32 v151, 0xffff0000, v58
	v_lshlrev_b32_e32 v152, 16, v59
	v_and_b32_e32 v153, 0xffff0000, v59
	s_cbranch_vccnz .LBB0_371
	v_lshl_add_u64 v[56:57], v[88:89], 0, s[56:57]
	ds_read_b128 v[52:55], v246 offset:4096
	s_waitcnt lgkmcnt(0)
	v_lshlrev_b32_e32 v58, 16, v52
	v_and_b32_e32 v59, 0xffff0000, v52
	v_lshlrev_b32_e32 v60, 16, v53
	v_and_b32_e32 v61, 0xffff0000, v53
	v_mul_f32_e32 v52, 0xbfb8aa3b, v58
	v_mul_f32_e32 v53, 0xbfb8aa3b, v59
	v_exp_f32_e32 v52, v52
	v_exp_f32_e32 v53, v53
	v_lshlrev_b32_e32 v62, 16, v54
	v_and_b32_e32 v54, 0xffff0000, v54
	v_add_f32_e32 v52, 1.0, v52
	v_add_f32_e32 v53, 1.0, v53
	v_rcp_f32_e32 v52, v52
	v_rcp_f32_e32 v53, v53
	v_lshlrev_b32_e32 v63, 16, v55
	v_and_b32_e32 v55, 0xffff0000, v55
	v_pk_mul_f32 v[154:155], v[52:53], v[154:155]
	v_mul_f32_e32 v52, 0xbfb8aa3b, v60
	v_mul_f32_e32 v53, 0xbfb8aa3b, v61
	v_exp_f32_e32 v52, v52
	v_exp_f32_e32 v53, v53
	v_add_f32_e32 v52, 1.0, v52
	v_add_f32_e32 v53, 1.0, v53
	v_rcp_f32_e32 v52, v52
	v_rcp_f32_e32 v53, v53
	s_nop 0
	v_pk_mul_f32 v[156:157], v[52:53], v[156:157]
	v_mul_f32_e32 v52, 0xbfb8aa3b, v62
	v_mul_f32_e32 v53, 0xbfb8aa3b, v54
	v_exp_f32_e32 v52, v52
	v_exp_f32_e32 v53, v53
	v_add_f32_e32 v52, 1.0, v52
	v_add_f32_e32 v53, 1.0, v53
	v_rcp_f32_e32 v52, v52
	v_rcp_f32_e32 v53, v53
	s_nop 0
	v_pk_mul_f32 v[142:143], v[52:53], v[142:143]
	v_mul_f32_e32 v52, 0xbfb8aa3b, v63
	v_mul_f32_e32 v53, 0xbfb8aa3b, v55
	v_exp_f32_e32 v52, v52
	v_exp_f32_e32 v53, v53
	v_add_f32_e32 v52, 1.0, v52
	v_add_f32_e32 v53, 1.0, v53
	v_rcp_f32_e32 v52, v52
	v_rcp_f32_e32 v53, v53
	s_nop 0
	v_pk_mul_f32 v[144:145], v[52:53], v[144:145]
	ds_read_b128 v[52:55], v246 offset:5120
	s_waitcnt lgkmcnt(0)
	v_lshlrev_b32_e32 v56, 16, v52
	v_and_b32_e32 v57, 0xffff0000, v52
	v_lshlrev_b32_e32 v58, 16, v53
	v_and_b32_e32 v59, 0xffff0000, v53
	v_mul_f32_e32 v52, 0xbfb8aa3b, v56
	v_mul_f32_e32 v53, 0xbfb8aa3b, v57
	v_exp_f32_e32 v52, v52
	v_exp_f32_e32 v53, v53
	v_lshlrev_b32_e32 v60, 16, v54
	v_and_b32_e32 v54, 0xffff0000, v54
	v_add_f32_e32 v52, 1.0, v52
	v_add_f32_e32 v53, 1.0, v53
	v_rcp_f32_e32 v52, v52
	v_rcp_f32_e32 v53, v53
	v_lshlrev_b32_e32 v61, 16, v55
	v_and_b32_e32 v55, 0xffff0000, v55
	v_pk_mul_f32 v[146:147], v[52:53], v[146:147]
	v_mul_f32_e32 v52, 0xbfb8aa3b, v58
	v_mul_f32_e32 v53, 0xbfb8aa3b, v59
	v_exp_f32_e32 v52, v52
	v_exp_f32_e32 v53, v53
	v_add_f32_e32 v52, 1.0, v52
	v_add_f32_e32 v53, 1.0, v53
	v_rcp_f32_e32 v52, v52
	v_rcp_f32_e32 v53, v53
	s_nop 0
	v_pk_mul_f32 v[148:149], v[52:53], v[148:149]
	v_mul_f32_e32 v52, 0xbfb8aa3b, v60
	v_mul_f32_e32 v53, 0xbfb8aa3b, v54
	v_exp_f32_e32 v52, v52
	v_exp_f32_e32 v53, v53
	v_add_f32_e32 v52, 1.0, v52
	v_add_f32_e32 v53, 1.0, v53
	v_rcp_f32_e32 v52, v52
	v_rcp_f32_e32 v53, v53
	s_nop 0
	v_pk_mul_f32 v[150:151], v[52:53], v[150:151]
	v_mul_f32_e32 v52, 0xbfb8aa3b, v61
	v_mul_f32_e32 v53, 0xbfb8aa3b, v55
	v_exp_f32_e32 v52, v52
	v_exp_f32_e32 v53, v53
	v_add_f32_e32 v52, 1.0, v52
	v_add_f32_e32 v53, 1.0, v53
	v_rcp_f32_e32 v52, v52
	v_rcp_f32_e32 v53, v53
	s_nop 0
	v_pk_mul_f32 v[152:153], v[52:53], v[152:153]

.LBB0_374:
	s_and_b64 vcc, exec, s[42:43]
	s_waitcnt vmcnt(4)
	v_mov_b32_e32 v68, v220
	v_mov_b32_e32 v69, v221
	v_mov_b32_e32 v70, v222
	v_mov_b32_e32 v71, v223
	v_mov_b32_e32 v72, v224
	v_mov_b32_e32 v73, v225
	v_mov_b32_e32 v74, v226
	v_mov_b32_e32 v75, v227
	v_lshlrev_b32_e32 v170, 16, v68
	v_and_b32_e32 v171, 0xffff0000, v68
	v_lshlrev_b32_e32 v172, 16, v69
	v_and_b32_e32 v173, 0xffff0000, v69
	v_lshlrev_b32_e32 v158, 16, v70
	v_and_b32_e32 v159, 0xffff0000, v70
	v_lshlrev_b32_e32 v160, 16, v71
	v_and_b32_e32 v161, 0xffff0000, v71
	s_waitcnt vmcnt(4)
	v_lshlrev_b32_e32 v162, 16, v72
	v_and_b32_e32 v163, 0xffff0000, v72
	v_lshlrev_b32_e32 v164, 16, v73
	v_and_b32_e32 v165, 0xffff0000, v73
	v_lshlrev_b32_e32 v166, 16, v74
	v_and_b32_e32 v167, 0xffff0000, v74
	v_lshlrev_b32_e32 v168, 16, v75
	v_and_b32_e32 v169, 0xffff0000, v75
	s_cbranch_vccnz .LBB0_376
	v_lshl_add_u64 v[72:73], v[88:89], 0, s[58:59]
	ds_read_b128 v[68:71], v246 offset:6144
	s_waitcnt lgkmcnt(0)
	v_lshlrev_b32_e32 v74, 16, v68
	v_and_b32_e32 v75, 0xffff0000, v68
	v_lshlrev_b32_e32 v76, 16, v69
	v_and_b32_e32 v77, 0xffff0000, v69
	v_mul_f32_e32 v68, 0xbfb8aa3b, v74
	v_mul_f32_e32 v69, 0xbfb8aa3b, v75
	v_exp_f32_e32 v68, v68
	v_exp_f32_e32 v69, v69
	v_lshlrev_b32_e32 v78, 16, v70
	v_and_b32_e32 v70, 0xffff0000, v70
	v_add_f32_e32 v68, 1.0, v68
	v_add_f32_e32 v69, 1.0, v69
	v_rcp_f32_e32 v68, v68
	v_rcp_f32_e32 v69, v69
	v_lshlrev_b32_e32 v79, 16, v71
	v_and_b32_e32 v71, 0xffff0000, v71
	v_pk_mul_f32 v[170:171], v[68:69], v[170:171]
	v_mul_f32_e32 v68, 0xbfb8aa3b, v76
	v_mul_f32_e32 v69, 0xbfb8aa3b, v77
	v_exp_f32_e32 v68, v68
	v_exp_f32_e32 v69, v69
	v_add_f32_e32 v68, 1.0, v68
	v_add_f32_e32 v69, 1.0, v69
	v_rcp_f32_e32 v68, v68
	v_rcp_f32_e32 v69, v69
	s_nop 0
	v_pk_mul_f32 v[172:173], v[68:69], v[172:173]
	v_mul_f32_e32 v68, 0xbfb8aa3b, v78
	v_mul_f32_e32 v69, 0xbfb8aa3b, v70
	v_exp_f32_e32 v68, v68
	v_exp_f32_e32 v69, v69
	v_add_f32_e32 v68, 1.0, v68
	v_add_f32_e32 v69, 1.0, v69
	v_rcp_f32_e32 v68, v68
	v_rcp_f32_e32 v69, v69
	s_nop 0
	v_pk_mul_f32 v[158:159], v[68:69], v[158:159]
	v_mul_f32_e32 v68, 0xbfb8aa3b, v79
	v_mul_f32_e32 v69, 0xbfb8aa3b, v71
	v_exp_f32_e32 v68, v68
	v_exp_f32_e32 v69, v69
	v_add_f32_e32 v68, 1.0, v68
	v_add_f32_e32 v69, 1.0, v69
	v_rcp_f32_e32 v68, v68
	v_rcp_f32_e32 v69, v69
	s_nop 0
	v_pk_mul_f32 v[160:161], v[68:69], v[160:161]
	ds_read_b128 v[68:71], v246 offset:7168
	s_waitcnt lgkmcnt(0)
	v_lshlrev_b32_e32 v72, 16, v68
	v_and_b32_e32 v73, 0xffff0000, v68
	v_lshlrev_b32_e32 v74, 16, v69
	v_and_b32_e32 v75, 0xffff0000, v69
	v_mul_f32_e32 v68, 0xbfb8aa3b, v72
	v_mul_f32_e32 v69, 0xbfb8aa3b, v73
	v_exp_f32_e32 v68, v68
	v_exp_f32_e32 v69, v69
	v_lshlrev_b32_e32 v76, 16, v70
	v_and_b32_e32 v70, 0xffff0000, v70
	v_add_f32_e32 v68, 1.0, v68
	v_add_f32_e32 v69, 1.0, v69
	v_rcp_f32_e32 v68, v68
	v_rcp_f32_e32 v69, v69
	v_lshlrev_b32_e32 v77, 16, v71
	v_and_b32_e32 v71, 0xffff0000, v71
	v_pk_mul_f32 v[162:163], v[68:69], v[162:163]
	v_mul_f32_e32 v68, 0xbfb8aa3b, v74
	v_mul_f32_e32 v69, 0xbfb8aa3b, v75
	v_exp_f32_e32 v68, v68
	v_exp_f32_e32 v69, v69
	v_add_f32_e32 v68, 1.0, v68
	v_add_f32_e32 v69, 1.0, v69
	v_rcp_f32_e32 v68, v68
	v_rcp_f32_e32 v69, v69
	s_nop 0
	v_pk_mul_f32 v[164:165], v[68:69], v[164:165]
	v_mul_f32_e32 v68, 0xbfb8aa3b, v76
	v_mul_f32_e32 v69, 0xbfb8aa3b, v70
	v_exp_f32_e32 v68, v68
	v_exp_f32_e32 v69, v69
	v_add_f32_e32 v68, 1.0, v68
	v_add_f32_e32 v69, 1.0, v69
	v_rcp_f32_e32 v68, v68
	v_rcp_f32_e32 v69, v69
	s_nop 0
	v_pk_mul_f32 v[166:167], v[68:69], v[166:167]
	v_mul_f32_e32 v68, 0xbfb8aa3b, v77
	v_mul_f32_e32 v69, 0xbfb8aa3b, v71
	v_exp_f32_e32 v68, v68
	v_exp_f32_e32 v69, v69
	v_add_f32_e32 v68, 1.0, v68
	v_add_f32_e32 v69, 1.0, v69
	v_rcp_f32_e32 v68, v68
	v_rcp_f32_e32 v69, v69
	s_nop 0
	v_pk_mul_f32 v[168:169], v[68:69], v[168:169]
